# half of the blocks start the MLP-up GEMM ~15us late so the epilogue store bursts of the two halves interleave
# speedup vs baseline: 1.1008x; 1.0023x over previous
.LBB0_2337:
	s_or_b64 exec, exec, s[2:3]
	s_mov_b64 s[6:7], s[0:1]
	s_mov_b32 s60, s90
	s_mov_b32 s62, s14
	s_mov_b32 s61, s33
	s_waitcnt lgkmcnt(0)
	s_barrier
	s_bitcmp1_b32 s14, 3
	s_cbranch_scc0 .Lnodelay13
	s_sleep 127
	s_sleep 127
	s_sleep 127
	s_sleep 127
.Lnodelay13:
	v_mbcnt_lo_u32_b32 v6, -1, 0
	v_mbcnt_hi_u32_b32 v6, -1, v6
	s_load_dwordx4 s[16:19], s[6:7], 0x118
	s_add_i32 s12, s40, 1
	s_cmp_eq_u32 s40, 3
	s_cselect_b64 s[42:43], -1, 0
	s_and_b64 vcc, exec, s[42:43]
	s_cbranch_vccnz .LBB0_2407
	s_lshl_b32 s63, s62, 3
	s_add_i32 s63, s63, s61
	s_cmpk_gt_i32 s63, 0x60f
	s_mov_b32 s13, s23
	s_cbranch_scc1 .LBB0_2364
	s_load_dwordx2 s[2:3], s[6:7], 0xc8
	s_load_dwordx2 s[8:9], s[6:7], 0x28
	s_lshl_b32 s41, s60, 3
	s_lshl_b64 s[4:5], s[12:13], 22
	v_lshlrev_b32_e32 v0, 4, v6
	s_waitcnt lgkmcnt(0)
	s_add_u32 s2, s2, s4
	v_lshlrev_b32_e32 v2, 3, v6
	s_addc_u32 s3, s3, s5
	s_mul_i32 s4, s40, 0x820000
	v_and_b32_e32 v0, 0x70, v0
	v_and_b32_e32 v2, 56, v2
	s_mul_hi_u32 s10, s40, 0x820000
	s_add_u32 s4, s8, s4
	v_ashrrev_i32_e32 v8, 3, v6
	v_lshl_add_u64 v[10:11], s[2:3], 0, v[0:1]
	s_movk_i32 s2, 0x84
	v_mul_u32_u24_e32 v9, 0x84, v2
	v_lshlrev_b32_e32 v2, 1, v2
	v_mov_b32_e32 v3, v1
	s_addc_u32 s5, s9, s10
	s_lshl_b32 s8, s61, 14
	v_mul_lo_u32 v5, v8, s2
	v_lshl_add_u64 v[2:3], s[18:19], 0, v[2:3]
	s_mov_b64 s[2:3], 0x720000
	s_add_i32 s8, s8, 0
	v_lshl_add_u64 v[12:13], v[2:3], 0, s[2:3]
	s_mov_b64 s[2:3], 0x100000
	s_lshl_b32 s22, s12, 10
	v_add_u32_e32 v4, s8, v0
	v_lshlrev_b32_e32 v14, 2, v8
	v_lshl_add_u64 v[16:17], v[2:3], 0, s[2:3]
	s_lshl_b32 s2, s63, 1
	v_add_u32_e32 v7, 8, v8
	v_add_u32_e32 v30, 16, v8
	v_add_u32_e32 v31, 24, v8
	v_add_u32_e32 v32, 32, v8
	v_add_u32_e32 v33, 40, v8
	v_add_u32_e32 v34, 48, v8
	v_add_u32_e32 v35, 56, v8
	v_add3_u32 v36, s8, v9, v14
	v_lshl_add_u64 v[14:15], s[4:5], 0, v[0:1]
	v_ashrrev_i32_e32 v9, 31, v8
	s_lshl_b32 s48, s63, 5
	s_lshl_b32 s49, s60, 8
	s_add_i32 s50, s2, 0xfffff7e0
	s_lshl_b32 s51, s60, 4
	s_lshl_b64 s[4:5], s[22:23], 2
	v_add_u32_e32 v37, v4, v5
	s_mov_b32 s52, s63
	s_branch .LBB0_2342
